# out-proj K-loop: the eight per-block s_setprio flips removed, one static s_setprio 1 for waves 4-7 before the loop and s_setprio 0 after it
# speedup vs baseline: 1.0064x; 1.0046x over previous
;     __device__ __forceinline__ bool next(int i, Unit& u) const { if (i) return false; u.pm = pm; u.pn = pn; return true; }
; #define PG8_WAIT_V(n) asm volatile("s_waitcnt vmcnt(" #n ")" ::: "memory")
; template <class Epi, class Sched, bool ALIGN_EPI, bool SP2>
; __device__ __forceinline__ void gemm_phase(LAS unsigned char* lds, const Gemm g, const Sched& S, const Epi& E, int tid_in) {
;     ...
;     for (;;) {
;         const bool has_next = S.next(ui + 1, nxt);
;         const unsigned nA = has_next ? (unsigned)nxt.pm * tstepA : cA, nB = has_next ? (unsigned)nxt.pn * tstepB : cB;
;         for (int t = 0; t < nt; t += 2) {
;             const bool last = (t == nt - 2);
;             const unsigned a1 = cA + (unsigned)(t + 1) * kstep;
;             const unsigned a2 = last ? nA : cA + (unsigned)(t + 2) * kstep, b2 = last ? nB : cB + (unsigned)(t + 2) * kstep;
;             const unsigned a3 = a2 + kstep, b3 = b2 + kstep;
;             if constexpr (Epi::MIDK) { if (t == g.kmid) E.midk(acc, wr, fr); }
;             if constexpr (SP2) {
;             PG8_LDB(B0, 0, 0); PG8_LDB(B1, 0, 1); PG8_SCHED; PG8_LDA(At, 0, 0); PG8_STAGE(PG8_SA(1, 1), a1 + hstepA, voffA);
;             PG8_WAIT_V(8); PG8_WAIT_L(0); PG8_BAR; PG8_MMA(0, 0, At, B0); PG8_MMA(0, 1, At, B1); PG8_BAR; PG8_SCHED;
;             PG8_LDA(At, 0, 1); PG8_STAGE(PG8_SB(0, 0), b2, voffB); PG8_STAGE(PG8_SB(0, 1), b2 + hstepB, voffB); PG8_STAGE(PG8_SA(0, 0), a2, voffA);
;             PG8_WAIT_V(8); PG8_WAIT_L(0); PG8_BAR; PG8_MMA(1, 0, At, B0); PG8_MMA(1, 1, At, B1); PG8_BAR; PG8_SCHED;
;             PG8_LDB(B0, 1, 0); PG8_LDB(B1, 1, 1); PG8_SCHED; PG8_LDA(At, 1, 0); PG8_STAGE(PG8_SA(0, 1), a2 + hstepA, voffA);
;             PG8_WAIT_V(8); PG8_WAIT_L(0); PG8_BAR; PG8_MMA(0, 0, At, B0); PG8_MMA(0, 1, At, B1); PG8_BAR; PG8_SCHED;
;             PG8_LDA(At, 1, 1); PG8_STAGE(PG8_SB(1, 0), b3, voffB); PG8_STAGE(PG8_SB(1, 1), b3 + hstepB, voffB); PG8_STAGE(PG8_SA(1, 0), a3, voffA);
;             PG8_WAIT_V(8); PG8_WAIT_L(0); PG8_BAR; PG8_MMA(1, 0, At, B0); PG8_MMA(1, 1, At, B1); PG8_BAR; PG8_SCHED;
;     ...
; #pragma unroll
;         for (int a = 0; a < 2; ++a)
; #pragma unroll
;             for (int b = 0; b < 2; ++b)
; #pragma unroll
;                 for (int m = 0; m < 4; ++m)
; #pragma unroll
;                     for (int n = 0; n < 2; ++n) acc[a][b][m][n] = (f32x4){0.f, 0.f, 0.f, 0.f};
.LBB0_337:
	s_lshl_b32 s53, s52, 21
	s_and_b64 s[4:5], s[36:37], exec
	s_cselect_b32 s4, s53, s57
	s_lshl_b32 s54, s50, 21
	s_and_b64 s[14:15], s[36:37], exec
	v_mov_b32_e32 v2, 0
	s_cselect_b32 s5, s54, s58
	s_add_i32 s57, s57, 0x100080
	s_addk_i32 s58, 0x100
	s_mov_b32 s59, -2
	v_mov_b32_e32 v3, v2
	v_mov_b32_e32 v4, v2
	v_mov_b32_e32 v5, v2
	v_mov_b32_e32 v6, v2
	v_mov_b32_e32 v7, v2
	v_mov_b32_e32 v8, v2
	v_mov_b32_e32 v9, v2
	v_mov_b32_e32 v14, v2
	v_mov_b32_e32 v15, v2
	v_mov_b32_e32 v16, v2
	v_mov_b32_e32 v17, v2
	v_mov_b32_e32 v22, v2
	v_mov_b32_e32 v23, v2
	v_mov_b32_e32 v24, v2
	v_mov_b32_e32 v25, v2
	v_mov_b32_e32 v30, v2
	v_mov_b32_e32 v31, v2
	v_mov_b32_e32 v32, v2
	v_mov_b32_e32 v33, v2
	v_mov_b32_e32 v38, v2
	v_mov_b32_e32 v39, v2
	v_mov_b32_e32 v40, v2
	v_mov_b32_e32 v41, v2
	v_mov_b32_e32 v46, v2
	v_mov_b32_e32 v47, v2
	v_mov_b32_e32 v48, v2
	v_mov_b32_e32 v49, v2
	v_mov_b32_e32 v54, v2
	v_mov_b32_e32 v55, v2
	v_mov_b32_e32 v56, v2
	v_mov_b32_e32 v57, v2
	v_mov_b32_e32 v10, v2
	v_mov_b32_e32 v11, v2
	v_mov_b32_e32 v12, v2
	v_mov_b32_e32 v13, v2
	v_mov_b32_e32 v18, v2
	v_mov_b32_e32 v19, v2
	v_mov_b32_e32 v20, v2
	v_mov_b32_e32 v21, v2
	v_mov_b32_e32 v26, v2
	v_mov_b32_e32 v27, v2
	v_mov_b32_e32 v28, v2
	v_mov_b32_e32 v29, v2
	v_mov_b32_e32 v34, v2
	v_mov_b32_e32 v35, v2
	v_mov_b32_e32 v36, v2
	v_mov_b32_e32 v37, v2
	v_mov_b32_e32 v42, v2
	v_mov_b32_e32 v43, v2
	v_mov_b32_e32 v44, v2
	v_mov_b32_e32 v45, v2
	v_mov_b32_e32 v50, v2
	v_mov_b32_e32 v51, v2
	v_mov_b32_e32 v52, v2
	v_mov_b32_e32 v53, v2
	v_mov_b32_e32 v58, v2
	v_mov_b32_e32 v59, v2
	v_mov_b32_e32 v60, v2
	v_mov_b32_e32 v61, v2
	v_mov_b32_e32 v62, v2
	v_mov_b32_e32 v63, v2
	v_mov_b32_e32 v64, v2
	v_mov_b32_e32 v65, v2
	v_mov_b32_e32 v66, v2
	v_mov_b32_e32 v67, v2
	v_mov_b32_e32 v68, v2
	v_mov_b32_e32 v69, v2
	v_mov_b32_e32 v70, v2
	v_mov_b32_e32 v71, v2
	v_mov_b32_e32 v72, v2
	v_mov_b32_e32 v73, v2
	v_mov_b32_e32 v78, v2
	v_mov_b32_e32 v79, v2
	v_mov_b32_e32 v80, v2
	v_mov_b32_e32 v81, v2
	v_mov_b32_e32 v86, v2
	v_mov_b32_e32 v87, v2
	v_mov_b32_e32 v88, v2
	v_mov_b32_e32 v89, v2
	v_mov_b32_e32 v94, v2
	v_mov_b32_e32 v95, v2
	v_mov_b32_e32 v96, v2
	v_mov_b32_e32 v97, v2
	v_mov_b32_e32 v102, v2
	v_mov_b32_e32 v103, v2
	v_mov_b32_e32 v104, v2
	v_mov_b32_e32 v105, v2
	v_mov_b32_e32 v110, v2
	v_mov_b32_e32 v111, v2
	v_mov_b32_e32 v112, v2
	v_mov_b32_e32 v113, v2
	v_mov_b32_e32 v120, v2
	v_mov_b32_e32 v121, v2
	v_mov_b32_e32 v122, v2
	v_mov_b32_e32 v123, v2
	v_mov_b32_e32 v74, v2
	v_mov_b32_e32 v75, v2
	v_mov_b32_e32 v76, v2
	v_mov_b32_e32 v77, v2
	v_mov_b32_e32 v82, v2
	v_mov_b32_e32 v83, v2
	v_mov_b32_e32 v84, v2
	v_mov_b32_e32 v85, v2
	v_mov_b32_e32 v90, v2
	v_mov_b32_e32 v91, v2
	v_mov_b32_e32 v92, v2
	v_mov_b32_e32 v93, v2
	v_mov_b32_e32 v98, v2
	v_mov_b32_e32 v99, v2
	v_mov_b32_e32 v100, v2
	v_mov_b32_e32 v101, v2
	v_mov_b32_e32 v106, v2
	v_mov_b32_e32 v107, v2
	v_mov_b32_e32 v108, v2
	v_mov_b32_e32 v109, v2
	v_mov_b32_e32 v116, v2
	v_mov_b32_e32 v117, v2
	v_mov_b32_e32 v118, v2
	v_mov_b32_e32 v119, v2
	v_mov_b32_e32 v124, v2
	v_mov_b32_e32 v125, v2
	v_mov_b32_e32 v126, v2
	v_mov_b32_e32 v127, v2
	v_mov_b32_e32 v128, v2
	v_mov_b32_e32 v129, v2
	v_mov_b32_e32 v130, v2
	v_mov_b32_e32 v131, v2
	s_and_b64 vcc, exec, s[44:45]
	s_cbranch_vccnz .Lop_skip
	s_setprio 1
.Lop_skip:
.LBB0_338:
	v_add_u32_e32 v144, 0x10000, v154
	v_add_u32_e32 v148, 0x14000, v154
	ds_read_b128 v[132:135], v144
	ds_read_b128 v[136:139], v144 offset:1024
	ds_read_b128 v[140:143], v144 offset:2048
	ds_read_b128 v[144:147], v144 offset:3072
	ds_read_b128 v[156:159], v148
	ds_read_b128 v[160:163], v148 offset:1024
	ds_read_b128 v[164:167], v148 offset:2048
	ds_read_b128 v[168:171], v148 offset:3072
	s_add_i32 s14, s57, 0xfff00080
	s_cmp_eq_u32 s59, 60
	s_cselect_b32 s14, s4, s14
	s_cselect_b32 s61, s5, s58
	s_or_b32 s60, s14, 0x80
	s_mov_b32 m0, s34
	ds_read_b128 v[172:175], v155
	ds_read_b128 v[176:179], v155 offset:1024
	ds_read_b128 v[180:183], v155 offset:2048
	ds_read_b128 v[184:187], v155 offset:3072
	ds_read_b128 v[188:191], v155 offset:4096
	ds_read_b128 v[192:195], v155 offset:5120
	ds_read_b128 v[196:199], v155 offset:6144
	ds_read_b128 v[200:203], v155 offset:7168
	buffer_load_dwordx4 v0, s[84:87], s57 offen lds
	s_mov_b32 m0, s47
	s_nop 0
	buffer_load_dwordx4 v150, s[84:87], s57 offen lds
	s_waitcnt vmcnt(8)
	s_waitcnt lgkmcnt(0)
	s_barrier
	s_waitcnt lgkmcnt(7)
	v_mfma_f32_16x16x32_bf16 v[128:131], v[132:135], v[172:175], v[128:131]
	v_mfma_f32_16x16x32_bf16 v[124:127], v[140:143], v[172:175], v[124:127]
	s_waitcnt lgkmcnt(5)
	v_mfma_f32_16x16x32_bf16 v[116:119], v[132:135], v[180:183], v[116:119]
	v_mfma_f32_16x16x32_bf16 v[106:109], v[140:143], v[180:183], v[106:109]
	s_waitcnt lgkmcnt(3)
	v_mfma_f32_16x16x32_bf16 v[98:101], v[132:135], v[188:191], v[98:101]
	v_mfma_f32_16x16x32_bf16 v[90:93], v[140:143], v[188:191], v[90:93]
	s_waitcnt lgkmcnt(1)
	v_mfma_f32_16x16x32_bf16 v[82:85], v[132:135], v[196:199], v[82:85]
	v_mfma_f32_16x16x32_bf16 v[74:77], v[140:143], v[196:199], v[74:77]
	v_mfma_f32_16x16x32_bf16 v[128:131], v[136:139], v[176:179], v[128:131]
	v_mfma_f32_16x16x32_bf16 v[124:127], v[144:147], v[176:179], v[124:127]
	v_mfma_f32_16x16x32_bf16 v[116:119], v[136:139], v[184:187], v[116:119]
	v_mfma_f32_16x16x32_bf16 v[106:109], v[144:147], v[184:187], v[106:109]
	v_mfma_f32_16x16x32_bf16 v[98:101], v[136:139], v[192:195], v[98:101]
	v_mfma_f32_16x16x32_bf16 v[90:93], v[144:147], v[192:195], v[90:93]
	s_waitcnt lgkmcnt(0)
	v_mfma_f32_16x16x32_bf16 v[82:85], v[136:139], v[200:203], v[82:85]
	v_mfma_f32_16x16x32_bf16 v[74:77], v[144:147], v[200:203], v[74:77]
	v_mfma_f32_16x16x32_bf16 v[120:123], v[156:159], v[172:175], v[120:123]
	v_mfma_f32_16x16x32_bf16 v[110:113], v[164:167], v[172:175], v[110:113]
	v_mfma_f32_16x16x32_bf16 v[102:105], v[156:159], v[180:183], v[102:105]
	v_mfma_f32_16x16x32_bf16 v[94:97], v[164:167], v[180:183], v[94:97]
	v_mfma_f32_16x16x32_bf16 v[86:89], v[156:159], v[188:191], v[86:89]
	v_mfma_f32_16x16x32_bf16 v[78:81], v[164:167], v[188:191], v[78:81]
	v_mfma_f32_16x16x32_bf16 v[70:73], v[156:159], v[196:199], v[70:73]
	v_mfma_f32_16x16x32_bf16 v[66:69], v[164:167], v[196:199], v[66:69]
	v_mfma_f32_16x16x32_bf16 v[120:123], v[160:163], v[176:179], v[120:123]
	v_mfma_f32_16x16x32_bf16 v[110:113], v[168:171], v[176:179], v[110:113]
	v_mfma_f32_16x16x32_bf16 v[102:105], v[160:163], v[184:187], v[102:105]
	v_mfma_f32_16x16x32_bf16 v[94:97], v[168:171], v[184:187], v[94:97]
	v_mfma_f32_16x16x32_bf16 v[86:89], v[160:163], v[192:195], v[86:89]
	v_mfma_f32_16x16x32_bf16 v[78:81], v[168:171], v[192:195], v[78:81]
	v_mfma_f32_16x16x32_bf16 v[70:73], v[160:163], v[200:203], v[70:73]
	v_mfma_f32_16x16x32_bf16 v[66:69], v[168:171], v[200:203], v[66:69]
	s_barrier
; #define PG8_STAGE(bufoff, goff, voff) do { _Pragma("unroll") for (int _i = 0; _i < 2; ++_i) \
;         __builtin_amdgcn_raw_ptr_buffer_load_lds(R_##voff, (LAS void*)(lds + (bufoff) + ldsw + _i * 8192), 16, (int)(voff)[_i], (int)(goff), 0, 0); } while (0)
; #define PG8_WAIT_V(n) asm volatile("s_waitcnt vmcnt(" #n ")" ::: "memory")
; #define PG8_WAIT_L(n) asm volatile("s_waitcnt lgkmcnt(" #n ")" ::: "memory")
; #define PG8_BAR __builtin_amdgcn_s_barrier()
; #define PG8_SCHED __builtin_amdgcn_sched_barrier(0)
; template <class Epi, class Sched, bool ALIGN_EPI, bool SP2>
; __device__ __forceinline__ void gemm_phase(LAS unsigned char* lds, const Gemm g, const Sched& S, const Epi& E, int tid_in) {
;     ...
;             PG8_LDB(B0, 0, 0); PG8_LDB(B1, 0, 1); PG8_SCHED; PG8_LDA(At, 0, 0); PG8_STAGE(PG8_SA(1, 1), a1 + hstepA, voffA);
;             PG8_WAIT_V(8); PG8_WAIT_L(0); PG8_BAR; PG8_MMA(0, 0, At, B0); PG8_MMA(0, 1, At, B1); PG8_BAR; PG8_SCHED;
;             PG8_LDA(At, 0, 1); PG8_STAGE(PG8_SB(0, 0), b2, voffB); PG8_STAGE(PG8_SB(0, 1), b2 + hstepB, voffB); PG8_STAGE(PG8_SA(0, 0), a2, voffA);
;             PG8_WAIT_V(8); PG8_WAIT_L(0); PG8_BAR; PG8_MMA(1, 0, At, B0); PG8_MMA(1, 1, At, B1); PG8_BAR; PG8_SCHED;
;             PG8_LDB(B0, 1, 0); PG8_LDB(B1, 1, 1); PG8_SCHED; PG8_LDA(At, 1, 0); PG8_STAGE(PG8_SA(0, 1), a2 + hstepA, voffA);
;             PG8_WAIT_V(8); PG8_WAIT_L(0); PG8_BAR; PG8_MMA(0, 0, At, B0); PG8_MMA(0, 1, At, B1); PG8_BAR; PG8_SCHED;
	s_mov_b32 m0, s8
	ds_read_b128 v[172:175], v155 offset:16384
	ds_read_b128 v[176:179], v155 offset:17408
	ds_read_b128 v[180:183], v155 offset:18432
	ds_read_b128 v[184:187], v155 offset:19456
	ds_read_b128 v[188:191], v155 offset:20480
	ds_read_b128 v[192:195], v155 offset:21504
	ds_read_b128 v[196:199], v155 offset:22528
	ds_read_b128 v[200:203], v155 offset:23552
	buffer_load_dwordx4 v115, s[40:43], s61 offen lds
	s_mov_b32 m0, s9
	s_add_i32 s15, s61, 0x40000
	buffer_load_dwordx4 v151, s[40:43], s61 offen lds
	s_mov_b32 m0, s10
	s_nop 0
	buffer_load_dwordx4 v115, s[40:43], s15 offen lds
	s_mov_b32 m0, s11
	s_nop 0
	buffer_load_dwordx4 v151, s[40:43], s15 offen lds
	s_mov_b32 m0, s7
	s_nop 0
	buffer_load_dwordx4 v0, s[84:87], s14 offen lds
	s_mov_b32 m0, s12
	s_nop 0
	buffer_load_dwordx4 v150, s[84:87], s14 offen lds
	s_waitcnt vmcnt(8)
	s_waitcnt lgkmcnt(0)
	s_barrier
	s_waitcnt lgkmcnt(7)
	v_mfma_f32_16x16x32_bf16 v[62:65], v[132:135], v[172:175], v[62:65]
	v_mfma_f32_16x16x32_bf16 v[58:61], v[140:143], v[172:175], v[58:61]
	s_waitcnt lgkmcnt(5)
	v_mfma_f32_16x16x32_bf16 v[50:53], v[132:135], v[180:183], v[50:53]
	v_mfma_f32_16x16x32_bf16 v[42:45], v[140:143], v[180:183], v[42:45]
	s_waitcnt lgkmcnt(3)
	v_mfma_f32_16x16x32_bf16 v[34:37], v[132:135], v[188:191], v[34:37]
	v_mfma_f32_16x16x32_bf16 v[26:29], v[140:143], v[188:191], v[26:29]
	s_waitcnt lgkmcnt(1)
	v_mfma_f32_16x16x32_bf16 v[18:21], v[132:135], v[196:199], v[18:21]
	v_mfma_f32_16x16x32_bf16 v[10:13], v[140:143], v[196:199], v[10:13]
	v_mfma_f32_16x16x32_bf16 v[62:65], v[136:139], v[176:179], v[62:65]
	v_mfma_f32_16x16x32_bf16 v[58:61], v[144:147], v[176:179], v[58:61]
	v_mfma_f32_16x16x32_bf16 v[50:53], v[136:139], v[184:187], v[50:53]
	v_mfma_f32_16x16x32_bf16 v[42:45], v[144:147], v[184:187], v[42:45]
	v_mfma_f32_16x16x32_bf16 v[34:37], v[136:139], v[192:195], v[34:37]
	v_mfma_f32_16x16x32_bf16 v[26:29], v[144:147], v[192:195], v[26:29]
	s_waitcnt lgkmcnt(0)
	v_mfma_f32_16x16x32_bf16 v[18:21], v[136:139], v[200:203], v[18:21]
	v_mfma_f32_16x16x32_bf16 v[10:13], v[144:147], v[200:203], v[10:13]
	v_mfma_f32_16x16x32_bf16 v[54:57], v[156:159], v[172:175], v[54:57]
	v_mfma_f32_16x16x32_bf16 v[46:49], v[164:167], v[172:175], v[46:49]
	v_mfma_f32_16x16x32_bf16 v[38:41], v[156:159], v[180:183], v[38:41]
	v_mfma_f32_16x16x32_bf16 v[30:33], v[164:167], v[180:183], v[30:33]
	v_mfma_f32_16x16x32_bf16 v[22:25], v[156:159], v[188:191], v[22:25]
	v_mfma_f32_16x16x32_bf16 v[14:17], v[164:167], v[188:191], v[14:17]
	v_mfma_f32_16x16x32_bf16 v[6:9], v[156:159], v[196:199], v[6:9]
	v_mfma_f32_16x16x32_bf16 v[2:5], v[164:167], v[196:199], v[2:5]
	v_mfma_f32_16x16x32_bf16 v[54:57], v[160:163], v[176:179], v[54:57]
	v_mfma_f32_16x16x32_bf16 v[46:49], v[168:171], v[176:179], v[46:49]
	v_mfma_f32_16x16x32_bf16 v[38:41], v[160:163], v[184:187], v[38:41]
	v_mfma_f32_16x16x32_bf16 v[30:33], v[168:171], v[184:187], v[30:33]
	v_mfma_f32_16x16x32_bf16 v[22:25], v[160:163], v[192:195], v[22:25]
	v_mfma_f32_16x16x32_bf16 v[14:17], v[168:171], v[192:195], v[14:17]
	v_mfma_f32_16x16x32_bf16 v[6:9], v[160:163], v[200:203], v[6:9]
	v_mfma_f32_16x16x32_bf16 v[2:5], v[168:171], v[200:203], v[2:5]
	s_barrier
	v_add_u32_e32 v144, 0x18000, v154
	v_add_u32_e32 v148, 0x1c000, v154
	ds_read_b128 v[132:135], v144
	ds_read_b128 v[136:139], v144 offset:1024
	ds_read_b128 v[140:143], v144 offset:2048
	ds_read_b128 v[144:147], v144 offset:3072
	ds_read_b128 v[156:159], v148
	ds_read_b128 v[160:163], v148 offset:1024
	ds_read_b128 v[164:167], v148 offset:2048
	ds_read_b128 v[168:171], v148 offset:3072
	s_add_i32 s14, s14, 0x100000
	s_mov_b32 m0, s13
	ds_read_b128 v[172:175], v155 offset:32768
	ds_read_b128 v[176:179], v155 offset:33792
	ds_read_b128 v[180:183], v155 offset:34816
	ds_read_b128 v[184:187], v155 offset:35840
	ds_read_b128 v[188:191], v155 offset:36864
	ds_read_b128 v[192:195], v155 offset:37888
	ds_read_b128 v[196:199], v155 offset:38912
	ds_read_b128 v[200:203], v155 offset:39936
	buffer_load_dwordx4 v0, s[84:87], s14 offen lds
	s_mov_b32 m0, s16
	s_nop 0
	buffer_load_dwordx4 v150, s[84:87], s14 offen lds
	s_waitcnt vmcnt(8)
	s_waitcnt lgkmcnt(0)
	s_barrier
; #define PG8_STAGE(bufoff, goff, voff) do { _Pragma("unroll") for (int _i = 0; _i < 2; ++_i) \
;         __builtin_amdgcn_raw_ptr_buffer_load_lds(R_##voff, (LAS void*)(lds + (bufoff) + ldsw + _i * 8192), 16, (int)(voff)[_i], (int)(goff), 0, 0); } while (0)
; #define PG8_WAIT_V(n) asm volatile("s_waitcnt vmcnt(" #n ")" ::: "memory")
; #define PG8_WAIT_L(n) asm volatile("s_waitcnt lgkmcnt(" #n ")" ::: "memory")
; #define PG8_BAR __builtin_amdgcn_s_barrier()
; #define PG8_SCHED __builtin_amdgcn_sched_barrier(0)
; template <class Epi, class Sched, bool ALIGN_EPI, bool SP2>
; __device__ __forceinline__ void gemm_phase(LAS unsigned char* lds, const Gemm g, const Sched& S, const Epi& E, int tid_in) {
;     ...
;             PG8_WAIT_V(8); PG8_WAIT_L(0); PG8_BAR; PG8_MMA(0, 0, At, B0); PG8_MMA(0, 1, At, B1); PG8_BAR; PG8_SCHED;
;             PG8_LDA(At, 1, 1); PG8_STAGE(PG8_SB(1, 0), b3, voffB); PG8_STAGE(PG8_SB(1, 1), b3 + hstepB, voffB); PG8_STAGE(PG8_SA(1, 0), a3, voffA);
;             PG8_WAIT_V(8); PG8_WAIT_L(0); PG8_BAR; PG8_MMA(1, 0, At, B0); PG8_MMA(1, 1, At, B1); PG8_BAR; PG8_SCHED;
	s_waitcnt lgkmcnt(7)
	v_mfma_f32_16x16x32_bf16 v[128:131], v[132:135], v[172:175], v[128:131]
	v_mfma_f32_16x16x32_bf16 v[124:127], v[140:143], v[172:175], v[124:127]
	s_waitcnt lgkmcnt(5)
	v_mfma_f32_16x16x32_bf16 v[116:119], v[132:135], v[180:183], v[116:119]
	v_mfma_f32_16x16x32_bf16 v[106:109], v[140:143], v[180:183], v[106:109]
	s_waitcnt lgkmcnt(3)
	v_mfma_f32_16x16x32_bf16 v[98:101], v[132:135], v[188:191], v[98:101]
	v_mfma_f32_16x16x32_bf16 v[90:93], v[140:143], v[188:191], v[90:93]
	s_waitcnt lgkmcnt(1)
	v_mfma_f32_16x16x32_bf16 v[82:85], v[132:135], v[196:199], v[82:85]
	v_mfma_f32_16x16x32_bf16 v[74:77], v[140:143], v[196:199], v[74:77]
	v_mfma_f32_16x16x32_bf16 v[128:131], v[136:139], v[176:179], v[128:131]
	v_mfma_f32_16x16x32_bf16 v[124:127], v[144:147], v[176:179], v[124:127]
	v_mfma_f32_16x16x32_bf16 v[116:119], v[136:139], v[184:187], v[116:119]
	v_mfma_f32_16x16x32_bf16 v[106:109], v[144:147], v[184:187], v[106:109]
	v_mfma_f32_16x16x32_bf16 v[98:101], v[136:139], v[192:195], v[98:101]
	v_mfma_f32_16x16x32_bf16 v[90:93], v[144:147], v[192:195], v[90:93]
	s_waitcnt lgkmcnt(0)
	v_mfma_f32_16x16x32_bf16 v[82:85], v[136:139], v[200:203], v[82:85]
	v_mfma_f32_16x16x32_bf16 v[74:77], v[144:147], v[200:203], v[74:77]
	v_mfma_f32_16x16x32_bf16 v[120:123], v[156:159], v[172:175], v[120:123]
	v_mfma_f32_16x16x32_bf16 v[110:113], v[164:167], v[172:175], v[110:113]
	v_mfma_f32_16x16x32_bf16 v[102:105], v[156:159], v[180:183], v[102:105]
	v_mfma_f32_16x16x32_bf16 v[94:97], v[164:167], v[180:183], v[94:97]
	v_mfma_f32_16x16x32_bf16 v[86:89], v[156:159], v[188:191], v[86:89]
	v_mfma_f32_16x16x32_bf16 v[78:81], v[164:167], v[188:191], v[78:81]
	v_mfma_f32_16x16x32_bf16 v[70:73], v[156:159], v[196:199], v[70:73]
	v_mfma_f32_16x16x32_bf16 v[66:69], v[164:167], v[196:199], v[66:69]
	v_mfma_f32_16x16x32_bf16 v[120:123], v[160:163], v[176:179], v[120:123]
	v_mfma_f32_16x16x32_bf16 v[110:113], v[168:171], v[176:179], v[110:113]
	v_mfma_f32_16x16x32_bf16 v[102:105], v[160:163], v[184:187], v[102:105]
	v_mfma_f32_16x16x32_bf16 v[94:97], v[168:171], v[184:187], v[94:97]
	v_mfma_f32_16x16x32_bf16 v[86:89], v[160:163], v[192:195], v[86:89]
	v_mfma_f32_16x16x32_bf16 v[78:81], v[168:171], v[192:195], v[78:81]
	v_mfma_f32_16x16x32_bf16 v[70:73], v[160:163], v[200:203], v[70:73]
	v_mfma_f32_16x16x32_bf16 v[66:69], v[168:171], v[200:203], v[66:69]
	s_barrier
	s_mov_b32 m0, s17
	s_or_b32 s14, s61, 0x80
	ds_read_b128 v[172:175], v155 offset:49152
	ds_read_b128 v[176:179], v155 offset:50176
	ds_read_b128 v[180:183], v155 offset:51200
	ds_read_b128 v[184:187], v155 offset:52224
	ds_read_b128 v[188:191], v155 offset:53248
	ds_read_b128 v[192:195], v155 offset:54272
	ds_read_b128 v[196:199], v155 offset:55296
	ds_read_b128 v[200:203], v155 offset:56320
	buffer_load_dwordx4 v115, s[40:43], s14 offen lds
	s_mov_b32 m0, s19
	s_add_i32 s61, s61, 0x40080
	buffer_load_dwordx4 v151, s[40:43], s14 offen lds
	s_mov_b32 m0, s29
	s_nop 0
	buffer_load_dwordx4 v115, s[40:43], s61 offen lds
	s_mov_b32 m0, s30
	s_nop 0
	buffer_load_dwordx4 v151, s[40:43], s61 offen lds
	s_mov_b32 m0, s25
	s_nop 0
	buffer_load_dwordx4 v0, s[84:87], s60 offen lds
	s_mov_b32 m0, s27
	s_nop 0
	buffer_load_dwordx4 v150, s[84:87], s60 offen lds
	s_waitcnt vmcnt(8)
	s_waitcnt lgkmcnt(0)
	s_barrier
	s_waitcnt lgkmcnt(7)
	v_mfma_f32_16x16x32_bf16 v[62:65], v[132:135], v[172:175], v[62:65]
	v_mfma_f32_16x16x32_bf16 v[58:61], v[140:143], v[172:175], v[58:61]
	s_waitcnt lgkmcnt(5)
	v_mfma_f32_16x16x32_bf16 v[50:53], v[132:135], v[180:183], v[50:53]
	v_mfma_f32_16x16x32_bf16 v[42:45], v[140:143], v[180:183], v[42:45]
	s_waitcnt lgkmcnt(3)
	v_mfma_f32_16x16x32_bf16 v[34:37], v[132:135], v[188:191], v[34:37]
	v_mfma_f32_16x16x32_bf16 v[26:29], v[140:143], v[188:191], v[26:29]
	s_waitcnt lgkmcnt(1)
	v_mfma_f32_16x16x32_bf16 v[18:21], v[132:135], v[196:199], v[18:21]
	v_mfma_f32_16x16x32_bf16 v[10:13], v[140:143], v[196:199], v[10:13]
	v_mfma_f32_16x16x32_bf16 v[62:65], v[136:139], v[176:179], v[62:65]
	v_mfma_f32_16x16x32_bf16 v[58:61], v[144:147], v[176:179], v[58:61]
	v_mfma_f32_16x16x32_bf16 v[50:53], v[136:139], v[184:187], v[50:53]
	v_mfma_f32_16x16x32_bf16 v[42:45], v[144:147], v[184:187], v[42:45]
	v_mfma_f32_16x16x32_bf16 v[34:37], v[136:139], v[192:195], v[34:37]
	v_mfma_f32_16x16x32_bf16 v[26:29], v[144:147], v[192:195], v[26:29]
	s_waitcnt lgkmcnt(0)
	v_mfma_f32_16x16x32_bf16 v[18:21], v[136:139], v[200:203], v[18:21]
	v_mfma_f32_16x16x32_bf16 v[10:13], v[144:147], v[200:203], v[10:13]
	v_mfma_f32_16x16x32_bf16 v[54:57], v[156:159], v[172:175], v[54:57]
	v_mfma_f32_16x16x32_bf16 v[46:49], v[164:167], v[172:175], v[46:49]
	v_mfma_f32_16x16x32_bf16 v[38:41], v[156:159], v[180:183], v[38:41]
	v_mfma_f32_16x16x32_bf16 v[30:33], v[164:167], v[180:183], v[30:33]
	v_mfma_f32_16x16x32_bf16 v[22:25], v[156:159], v[188:191], v[22:25]
	v_mfma_f32_16x16x32_bf16 v[14:17], v[164:167], v[188:191], v[14:17]
	v_mfma_f32_16x16x32_bf16 v[6:9], v[156:159], v[196:199], v[6:9]
	v_mfma_f32_16x16x32_bf16 v[2:5], v[164:167], v[196:199], v[2:5]
	v_mfma_f32_16x16x32_bf16 v[54:57], v[160:163], v[176:179], v[54:57]
	v_mfma_f32_16x16x32_bf16 v[46:49], v[168:171], v[176:179], v[46:49]
	v_mfma_f32_16x16x32_bf16 v[38:41], v[160:163], v[184:187], v[38:41]
	v_mfma_f32_16x16x32_bf16 v[30:33], v[168:171], v[184:187], v[30:33]
	v_mfma_f32_16x16x32_bf16 v[22:25], v[160:163], v[192:195], v[22:25]
	v_mfma_f32_16x16x32_bf16 v[14:17], v[168:171], v[192:195], v[14:17]
	v_mfma_f32_16x16x32_bf16 v[6:9], v[160:163], v[200:203], v[6:9]
	v_mfma_f32_16x16x32_bf16 v[2:5], v[168:171], v[200:203], v[2:5]
	s_barrier
	s_add_i32 s59, s59, 2
	s_addk_i32 s57, 0x100
	s_addk_i32 s58, 0x100
	s_cmp_gt_u32 s59, 61
	s_cbranch_scc0 .LBB0_338
	s_setprio 0
	s_and_b64 vcc, exec, s[44:45]
	s_cbranch_vccz .LBB0_341
	s_barrier
